# norm row loops (NORM1, NORM2W): all four x loads of a row issued together instead of exposing a second memory round trip
# speedup vs baseline: 1.0015x; 1.0015x over previous
.LBB0_1183:
	global_load_dwordx4 v[12:15], v21, s[8:9]
	global_load_dwordx4 v[8:11], v21, s[8:9] offset:1024
	global_load_dwordx4 v[4:7], v21, s[8:9] offset:2048
	global_load_dwordx4 v[40:43], v21, s[8:9] offset:3072
	s_lshl_b64 s[6:7], s[6:7], 2
	s_add_u32 s6, s12, s6
	s_addc_u32 s7, s13, s7
	s_waitcnt vmcnt(1)
	v_mul_f32_e32 v0, v13, v13
	v_mul_f32_e32 v1, v15, v15
	v_fmac_f32_e32 v0, v12, v12
	v_fmac_f32_e32 v1, v14, v14
	v_add_f32_e32 v0, v0, v1
	v_mul_f32_e32 v1, v9, v9
	v_mul_f32_e32 v2, v11, v11
	v_fmac_f32_e32 v1, v8, v8
	v_fmac_f32_e32 v2, v10, v10
	v_add_f32_e32 v1, v1, v2
	v_add_f32_e32 v0, v0, v1
	v_mul_f32_e32 v1, v5, v5
	v_mul_f32_e32 v2, v7, v7
	v_fmac_f32_e32 v1, v4, v4
	v_fmac_f32_e32 v2, v6, v6
	v_add_f32_e32 v1, v1, v2
	v_add_f32_e32 v20, v0, v1
	s_add_u32 s8, s6, 0x1000
	s_addc_u32 s9, s7, 0
	s_lshl_b64 s[10:11], s[10:11], 11
	s_waitcnt vmcnt(0)
	v_mul_f32_e32 v25, v41, v41
	v_mul_f32_e32 v26, v43, v43
	v_fmac_f32_e32 v25, v40, v40
	v_fmac_f32_e32 v26, v42, v42
	v_add_f32_e32 v25, v25, v26
	v_add_f32_e32 v20, v20, v25
	s_nop 1
	v_add_f32_dpp v20, v20, v20 quad_perm:[1,0,3,2] row_mask:0xf bank_mask:0xf bound_ctrl:1
	s_nop 1
	v_add_f32_dpp v20, v20, v20 quad_perm:[2,3,0,1] row_mask:0xf bank_mask:0xf bound_ctrl:1
	s_nop 1
	v_add_f32_dpp v20, v20, v20 row_half_mirror row_mask:0xf bank_mask:0xf bound_ctrl:1
	s_nop 1
	v_add_f32_dpp v20, v20, v20 row_mirror row_mask:0xf bank_mask:0xf bound_ctrl:1
	v_mov_b32_e32 v25, v20
	s_nop 1
	v_permlane16_swap_b32 v20, v25
	s_nop 1
	s_nop 0
	v_add_f32_e32 v20, v20, v25
	v_mov_b32_e32 v25, v20
	s_nop 1
	v_permlane32_swap_b32 v20, v25
	s_nop 1
	global_load_dwordx4 v[26:29], v[16:17], off
	global_load_dwordx4 v[30:33], v21, s[8:9]
	global_load_dwordx4 v[34:37], v21, s[6:7]
	v_add_f32_e32 v20, v20, v25
	v_fmamk_f32 v20, v20, 0x3a800000, v226
	v_cmp_gt_f32_e32 vcc, s82, v20
	v_mul_f32_e32 v25, 0x4b800000, v20
	s_nop 0
	v_cndmask_b32_e32 v20, v20, v25, vcc
	v_rsq_f32_e32 v20, v20
	s_nop 0
	v_mul_f32_e32 v25, 0x45800000, v20
	v_cndmask_b32_e32 v20, v20, v25, vcc
	v_pk_mul_f32 v[14:15], v[14:15], v[20:21] op_sel_hi:[1,0]
	v_pk_mul_f32 v[12:13], v[12:13], v[20:21] op_sel_hi:[1,0]
	v_pk_mul_f32 v[10:11], v[10:11], v[20:21] op_sel_hi:[1,0]
	v_pk_mul_f32 v[8:9], v[8:9], v[20:21] op_sel_hi:[1,0]
	v_pk_mul_f32 v[6:7], v[6:7], v[20:21] op_sel_hi:[1,0]
	v_pk_mul_f32 v[4:5], v[4:5], v[20:21] op_sel_hi:[1,0]
	v_pk_mul_f32 v[2:3], v[42:43], v[20:21] op_sel_hi:[1,0]
	v_pk_mul_f32 v[0:1], v[40:41], v[20:21] op_sel_hi:[1,0]
	s_waitcnt vmcnt(2)
	v_pk_mul_f32 v[12:13], v[26:27], v[12:13]
	v_pk_mul_f32 v[14:15], v[28:29], v[14:15]
	s_waitcnt vmcnt(1)
	v_pk_add_f32 v[28:29], v[30:31], 1.0 op_sel_hi:[1,0]
	v_pk_add_f32 v[26:27], v[32:33], 1.0 op_sel_hi:[1,0]
	s_waitcnt vmcnt(0)
	v_pk_fma_f32 v[12:13], v[28:29], v[12:13], v[34:35]
	v_lshl_add_u64 v[34:35], v[18:19], 0, s[10:11]
	v_pk_fma_f32 v[14:15], v[26:27], v[14:15], v[36:37]
	v_cvt_pk_bf16_f32 v12, v12, v13
	s_nop 0
	v_cvt_pk_bf16_f32 v13, v14, v15
	global_store_dwordx2 v[34:35], v[12:13], off
	global_load_dwordx4 v[12:15], v[16:17], off offset:1024
	s_nop 0
	global_load_dwordx4 v[26:29], v22, s[8:9]
	global_load_dwordx4 v[30:33], v21, s[6:7] offset:1024
	s_waitcnt vmcnt(2)
	v_pk_mul_f32 v[8:9], v[12:13], v[8:9]
	v_pk_mul_f32 v[10:11], v[14:15], v[10:11]
	s_waitcnt vmcnt(1)
	v_pk_add_f32 v[14:15], v[26:27], 1.0 op_sel_hi:[1,0]
	v_pk_add_f32 v[12:13], v[28:29], 1.0 op_sel_hi:[1,0]
	s_waitcnt vmcnt(0)
	v_pk_fma_f32 v[8:9], v[14:15], v[8:9], v[30:31]
	v_pk_fma_f32 v[10:11], v[12:13], v[10:11], v[32:33]
	v_cvt_pk_bf16_f32 v8, v8, v9
	s_nop 0
	v_cvt_pk_bf16_f32 v9, v10, v11
	global_store_dwordx2 v[34:35], v[8:9], off offset:512
	global_load_dwordx4 v[8:11], v[16:17], off offset:2048
	s_nop 0
	global_load_dwordx4 v[12:15], v23, s[8:9]
	global_load_dwordx4 v[26:29], v21, s[6:7] offset:2048
	s_waitcnt vmcnt(2)
	v_pk_mul_f32 v[4:5], v[4:5], v[8:9]
	v_pk_mul_f32 v[6:7], v[6:7], v[10:11]
	s_waitcnt vmcnt(1)
	v_pk_add_f32 v[10:11], v[12:13], 1.0 op_sel_hi:[1,0]
	v_pk_add_f32 v[8:9], v[14:15], 1.0 op_sel_hi:[1,0]
	s_waitcnt vmcnt(0)
	v_pk_fma_f32 v[4:5], v[4:5], v[10:11], v[26:27]
	v_pk_fma_f32 v[6:7], v[6:7], v[8:9], v[28:29]
	v_cvt_pk_bf16_f32 v4, v4, v5
	s_nop 0
	v_cvt_pk_bf16_f32 v5, v6, v7
	global_store_dwordx2 v[34:35], v[4:5], off offset:1024
	global_load_dwordx4 v[4:7], v[16:17], off offset:3072
	s_nop 0
	global_load_dwordx4 v[8:11], v24, s[8:9]
	global_load_dwordx4 v[12:15], v21, s[6:7] offset:3072
	v_readlane_b32 s6, v254, 22
	v_readlane_b32 s7, v254, 23
	s_add_u32 s4, s4, s6
	s_addc_u32 s5, s5, s7
	s_add_u32 s0, s0, s2
	s_addc_u32 s1, s1, s3
	s_cmpk_lt_i32 s4, 0x4200
	s_waitcnt vmcnt(2)
	v_pk_mul_f32 v[0:1], v[0:1], v[4:5]
	v_pk_mul_f32 v[2:3], v[2:3], v[6:7]
	s_waitcnt vmcnt(1)
	v_pk_add_f32 v[6:7], v[8:9], 1.0 op_sel_hi:[1,0]
	v_pk_add_f32 v[4:5], v[10:11], 1.0 op_sel_hi:[1,0]
	s_waitcnt vmcnt(0)
	v_pk_fma_f32 v[0:1], v[0:1], v[6:7], v[12:13]
	v_pk_fma_f32 v[2:3], v[2:3], v[4:5], v[14:15]
	v_cvt_pk_bf16_f32 v0, v0, v1
	s_nop 0
	v_cvt_pk_bf16_f32 v1, v2, v3
	global_store_dwordx2 v[34:35], v[0:1], off offset:1536
	s_cbranch_scc0 .LBB0_1188

.LBB0_1298:
	global_load_dwordx4 v[12:15], v21, s[8:9]
	global_load_dwordx4 v[8:11], v21, s[8:9] offset:1024
	global_load_dwordx4 v[4:7], v21, s[8:9] offset:2048
	global_load_dwordx4 v[40:43], v21, s[8:9] offset:3072
	s_lshl_b64 s[6:7], s[6:7], 2
	s_add_u32 s6, s14, s6
	s_addc_u32 s7, s15, s7
	s_waitcnt vmcnt(3)
	v_mul_f32_e32 v0, v13, v13
	v_mul_f32_e32 v1, v15, v15
	v_fmac_f32_e32 v0, v12, v12
	v_fmac_f32_e32 v1, v14, v14
	v_add_f32_e32 v0, v0, v1
	s_waitcnt vmcnt(2)
	v_mul_f32_e32 v1, v9, v9
	v_mul_f32_e32 v2, v11, v11
	v_fmac_f32_e32 v1, v8, v8
	v_fmac_f32_e32 v2, v10, v10
	v_add_f32_e32 v1, v1, v2
	v_add_f32_e32 v0, v0, v1
	s_waitcnt vmcnt(1)
	v_mul_f32_e32 v1, v5, v5
	v_mul_f32_e32 v2, v7, v7
	v_fmac_f32_e32 v1, v4, v4
	v_fmac_f32_e32 v2, v6, v6
	v_add_f32_e32 v1, v1, v2
	v_add_f32_e32 v20, v0, v1
	s_add_u32 s8, s6, 0x1000
	s_addc_u32 s9, s7, 0
	s_lshl_b64 s[10:11], s[10:11], 11
	s_waitcnt vmcnt(0)
	v_mul_f32_e32 v25, v41, v41
	v_mul_f32_e32 v26, v43, v43
	v_fmac_f32_e32 v25, v40, v40
	v_fmac_f32_e32 v26, v42, v42
	v_add_f32_e32 v25, v25, v26
	v_add_f32_e32 v20, v20, v25
	s_nop 1
	v_add_f32_dpp v20, v20, v20 quad_perm:[1,0,3,2] row_mask:0xf bank_mask:0xf bound_ctrl:1
	s_nop 1
	v_add_f32_dpp v20, v20, v20 quad_perm:[2,3,0,1] row_mask:0xf bank_mask:0xf bound_ctrl:1
	s_nop 1
	v_add_f32_dpp v20, v20, v20 row_half_mirror row_mask:0xf bank_mask:0xf bound_ctrl:1
	s_nop 1
	v_add_f32_dpp v20, v20, v20 row_mirror row_mask:0xf bank_mask:0xf bound_ctrl:1
	v_mov_b32_e32 v25, v20
	s_nop 1
	v_permlane16_swap_b32 v20, v25
	s_nop 1
	s_nop 0
	v_add_f32_e32 v20, v20, v25
	v_mov_b32_e32 v25, v20
	s_nop 1
	v_permlane32_swap_b32 v20, v25
	s_nop 1
	global_load_dwordx4 v[26:29], v[16:17], off
	global_load_dwordx4 v[30:33], v21, s[8:9]
	global_load_dwordx4 v[34:37], v21, s[6:7]
	v_add_f32_e32 v20, v20, v25
	v_fmamk_f32 v20, v20, 0x3a800000, v226
	v_cmp_gt_f32_e32 vcc, s82, v20
	v_mul_f32_e32 v25, 0x4b800000, v20
	s_nop 0
	v_cndmask_b32_e32 v20, v20, v25, vcc
	v_rsq_f32_e32 v20, v20
	s_nop 0
	v_mul_f32_e32 v25, 0x45800000, v20
	v_cndmask_b32_e32 v20, v20, v25, vcc
	v_pk_mul_f32 v[14:15], v[14:15], v[20:21] op_sel_hi:[1,0]
	v_pk_mul_f32 v[12:13], v[12:13], v[20:21] op_sel_hi:[1,0]
	v_pk_mul_f32 v[10:11], v[10:11], v[20:21] op_sel_hi:[1,0]
	v_pk_mul_f32 v[8:9], v[8:9], v[20:21] op_sel_hi:[1,0]
	v_pk_mul_f32 v[6:7], v[6:7], v[20:21] op_sel_hi:[1,0]
	v_pk_mul_f32 v[4:5], v[4:5], v[20:21] op_sel_hi:[1,0]
	v_pk_mul_f32 v[2:3], v[42:43], v[20:21] op_sel_hi:[1,0]
	v_pk_mul_f32 v[0:1], v[40:41], v[20:21] op_sel_hi:[1,0]
	s_waitcnt vmcnt(2)
	v_pk_mul_f32 v[12:13], v[26:27], v[12:13]
	v_pk_mul_f32 v[14:15], v[28:29], v[14:15]
	s_waitcnt vmcnt(1)
	v_pk_add_f32 v[28:29], v[30:31], 1.0 op_sel_hi:[1,0]
	v_pk_add_f32 v[26:27], v[32:33], 1.0 op_sel_hi:[1,0]
	s_waitcnt vmcnt(0)
	v_pk_fma_f32 v[12:13], v[28:29], v[12:13], v[34:35]
	v_lshl_add_u64 v[34:35], v[18:19], 0, s[10:11]
	v_pk_fma_f32 v[14:15], v[26:27], v[14:15], v[36:37]
	v_cvt_pk_bf16_f32 v12, v12, v13
	s_nop 0
	v_cvt_pk_bf16_f32 v13, v14, v15
	global_store_dwordx2 v[34:35], v[12:13], off
	global_load_dwordx4 v[12:15], v[16:17], off offset:1024
	s_nop 0
	global_load_dwordx4 v[26:29], v22, s[8:9]
	global_load_dwordx4 v[30:33], v21, s[6:7] offset:1024
	s_waitcnt vmcnt(2)
	v_pk_mul_f32 v[8:9], v[12:13], v[8:9]
	v_pk_mul_f32 v[10:11], v[14:15], v[10:11]
	s_waitcnt vmcnt(1)
	v_pk_add_f32 v[14:15], v[26:27], 1.0 op_sel_hi:[1,0]
	v_pk_add_f32 v[12:13], v[28:29], 1.0 op_sel_hi:[1,0]
	s_waitcnt vmcnt(0)
	v_pk_fma_f32 v[8:9], v[14:15], v[8:9], v[30:31]
	v_pk_fma_f32 v[10:11], v[12:13], v[10:11], v[32:33]
	v_cvt_pk_bf16_f32 v8, v8, v9
	s_nop 0
	v_cvt_pk_bf16_f32 v9, v10, v11
	global_store_dwordx2 v[34:35], v[8:9], off offset:512
	global_load_dwordx4 v[8:11], v[16:17], off offset:2048
	s_nop 0
	global_load_dwordx4 v[12:15], v23, s[8:9]
	global_load_dwordx4 v[26:29], v21, s[6:7] offset:2048
	s_waitcnt vmcnt(2)
	v_pk_mul_f32 v[4:5], v[4:5], v[8:9]
	v_pk_mul_f32 v[6:7], v[6:7], v[10:11]
	s_waitcnt vmcnt(1)
	v_pk_add_f32 v[10:11], v[12:13], 1.0 op_sel_hi:[1,0]
	v_pk_add_f32 v[8:9], v[14:15], 1.0 op_sel_hi:[1,0]
	s_waitcnt vmcnt(0)
	v_pk_fma_f32 v[4:5], v[4:5], v[10:11], v[26:27]
	v_pk_fma_f32 v[6:7], v[6:7], v[8:9], v[28:29]
	v_cvt_pk_bf16_f32 v4, v4, v5
	s_nop 0
	v_cvt_pk_bf16_f32 v5, v6, v7
	global_store_dwordx2 v[34:35], v[4:5], off offset:1024
	global_load_dwordx4 v[4:7], v[16:17], off offset:3072
	s_nop 0
	global_load_dwordx4 v[8:11], v24, s[8:9]
	global_load_dwordx4 v[12:15], v21, s[6:7] offset:3072
	v_readlane_b32 s6, v254, 22
	v_readlane_b32 s7, v254, 23
	s_add_u32 s4, s4, s6
	s_addc_u32 s5, s5, s7
	s_add_u32 s0, s0, s2
	s_addc_u32 s1, s1, s3
	s_cmpk_gt_i32 s4, 0x41ff
	s_waitcnt vmcnt(2)
	v_pk_mul_f32 v[0:1], v[0:1], v[4:5]
	v_pk_mul_f32 v[2:3], v[2:3], v[6:7]
	s_waitcnt vmcnt(1)
	v_pk_add_f32 v[6:7], v[8:9], 1.0 op_sel_hi:[1,0]
	v_pk_add_f32 v[4:5], v[10:11], 1.0 op_sel_hi:[1,0]
	s_waitcnt vmcnt(0)
	v_pk_fma_f32 v[0:1], v[0:1], v[6:7], v[12:13]
	v_pk_fma_f32 v[2:3], v[2:3], v[4:5], v[14:15]
	v_cvt_pk_bf16_f32 v0, v0, v1
	s_nop 0
	v_cvt_pk_bf16_f32 v1, v2, v3
	global_store_dwordx2 v[34:35], v[0:1], off offset:1536
	s_cbranch_scc1 .LBB0_1310
